# GEMM k-loop: each phase issues its LDS-DMA group before its LDS fragment reads
# baseline (speedup 1.0000x reference)
; #define PG8_STAGE(bufoff, gbase, voff) do { _Pragma("unroll") for (int _i = 0; _i < 2; ++_i) \
;         __builtin_amdgcn_global_load_lds((const unsigned*)((const char*)(gbase) + (voff)[_i]), (LAS unsigned*)(lds + (bufoff) + ldsw + _i * 8192), 16, 0, 0); } while (0)
; #define PG8_LDA(dst, b, h) do { _Pragma("unroll") for (int m = 0; m < 4; ++m) _Pragma("unroll") for (int k = 0; k < 2; ++k) dst[m][k] = *(const LAS bf16x8*)(lds + PG8_SA(b, h) + aoff + m * 2048 + k * 1024); } while (0)
; #define PG8_LDB(dst, b, h) do { _Pragma("unroll") for (int n = 0; n < 2; ++n) _Pragma("unroll") for (int k = 0; k < 2; ++k) dst[n][k] = *(const LAS bf16x8*)(lds + PG8_SB(b, h) + boff + n * 2048 + k * 1024); } while (0)
; #define PG8_MMA(ai, bj, At, Bt) do { __builtin_amdgcn_s_setprio(1); _Pragma("unroll") for (int m = 0; m < 4; ++m) _Pragma("unroll") for (int n = 0; n < 2; ++n) _Pragma("unroll") for (int k = 0; k < 2; ++k) \
;         acc[ai][bj][m][n] = __builtin_amdgcn_mfma_f32_16x16x32_bf16(Bt[n][k], At[m][k], acc[ai][bj][m][n], 0, 0, 0); __builtin_amdgcn_s_setprio(0); } while (0)
; #define PG8_WAIT_V(n) asm volatile("s_waitcnt vmcnt(" #n ")" ::: "memory")
; #define PG8_WAIT_L(n) asm volatile("s_waitcnt lgkmcnt(" #n ")" ::: "memory")
; #define PG8_BAR __builtin_amdgcn_s_barrier()
; #define PG8_SCHED __builtin_amdgcn_sched_barrier(0)
; template <class Epi>
; __device__ __forceinline__ void gemm_phase(LAS unsigned char* lds, const Gemm g, const StaticOrder& S, const Epi& E) {
;     ...
;         for (int t = 0; t < nt; t += 2) {
;             const bool last = (t == nt - 2);
;             const char* a1 = cA + (size_t)(t + 1) * kstep;
;             const char* a2 = last ? nA : cA + (size_t)(t + 2) * kstep; const char* b2 = last ? nB : cB + (size_t)(t + 2) * kstep;
;             const char* a3 = a2 + kstep; const char* b3 = b2 + kstep;
;             PG8_LDB(B0, 0, 0); PG8_LDB(B1, 0, 1); PG8_SCHED; PG8_LDA(At, 0, 0); PG8_STAGE(PG8_SA(1, 1), a1 + hstep, voffA);
;             PG8_WAIT_V(8); PG8_WAIT_L(0); PG8_BAR; PG8_MMA(0, 0, At, B0); PG8_MMA(0, 1, At, B1); PG8_BAR; PG8_SCHED;
;             PG8_LDA(At, 0, 1); PG8_STAGE(PG8_SB(0, 0), b2, voffB); PG8_STAGE(PG8_SB(0, 1), b2 + hstep, voffB); PG8_STAGE(PG8_SA(0, 0), a2, voffA);
;             PG8_WAIT_V(8); PG8_WAIT_L(0); PG8_BAR; PG8_MMA(1, 0, At, B0); PG8_MMA(1, 1, At, B1); PG8_BAR; PG8_SCHED;
.LBB0_221:
	v_add_u32_e32 v216, 0x10000, v245
	v_add_u32_e32 v217, 0x14000, v245
	v_add_u32_e32 v218, 0x18000, v245
	v_add_u32_e32 v219, 0x1c000, v245
	s_add_u32 s0, s6, 0x80
	s_addc_u32 s1, s7, 0
	s_add_u32 s6, s4, 0x100
	s_addc_u32 s7, s5, 0
	s_mov_b32 s4, 0
	s_waitcnt vmcnt(0)
	s_add_i32 s71, s4, 2
	s_add_u32 s72, s0, 0x80
	s_addc_u32 s5, s1, 0
	s_cmp_eq_u32 s62, s4
	s_cselect_b32 s5, s49, s5
	s_cselect_b32 s4, s48, s72
	s_cselect_b32 s73, s51, s7
	s_cselect_b32 s72, s50, s6
	s_add_u32 s74, s72, s2
	s_addc_u32 s75, s73, 0
	s_add_u32 vcc_lo, s4, s2
	s_addc_u32 vcc_hi, s5, 0
	s_add_i32 m0, s55, 0xc000
	s_nop 0
	global_load_lds_dwordx4 v208, s[0:1]
	s_add_i32 m0, s55, 0xe000
	s_nop 0
	global_load_lds_dwordx4 v210, s[0:1]
	ds_read_b128 v[128:131], v216
	ds_read_b128 v[132:135], v216 offset:1024
	ds_read_b128 v[136:139], v216 offset:2048
	ds_read_b128 v[140:143], v216 offset:3072
	ds_read_b128 v[144:147], v217
	ds_read_b128 v[148:151], v217 offset:1024
	ds_read_b128 v[152:155], v217 offset:2048
	ds_read_b128 v[156:159], v217 offset:3072
	ds_read_b128 v[160:163], v247
	ds_read_b128 v[164:167], v247 offset:1024
	ds_read_b128 v[168:171], v247 offset:2048
	ds_read_b128 v[172:175], v247 offset:3072
	ds_read_b128 v[176:179], v247 offset:4096
	ds_read_b128 v[180:183], v247 offset:5120
	ds_read_b128 v[184:187], v247 offset:6144
	ds_read_b128 v[188:191], v247 offset:7168
	s_waitcnt vmcnt(8)
	s_waitcnt lgkmcnt(0)
	s_barrier
	s_setprio 1
	s_waitcnt lgkmcnt(0)
	v_mfma_f32_16x16x32_bf16 v[124:127], v[128:131], v[160:163], 0
	v_mfma_f32_16x16x32_bf16 v[120:123], v[136:139], v[160:163], 0
	v_mfma_f32_16x16x32_bf16 v[108:111], v[128:131], v[168:171], 0
	v_mfma_f32_16x16x32_bf16 v[104:107], v[136:139], v[168:171], 0
	v_mfma_f32_16x16x32_bf16 v[92:95], v[128:131], v[176:179], 0
	v_mfma_f32_16x16x32_bf16 v[88:91], v[136:139], v[176:179], 0
	v_mfma_f32_16x16x32_bf16 v[76:79], v[128:131], v[184:187], 0
	v_mfma_f32_16x16x32_bf16 v[72:75], v[136:139], v[184:187], 0
	v_mfma_f32_16x16x32_bf16 v[124:127], v[132:135], v[164:167], v[124:127]
	v_mfma_f32_16x16x32_bf16 v[120:123], v[140:143], v[164:167], v[120:123]
	v_mfma_f32_16x16x32_bf16 v[108:111], v[132:135], v[172:175], v[108:111]
	v_mfma_f32_16x16x32_bf16 v[104:107], v[140:143], v[172:175], v[104:107]
	v_mfma_f32_16x16x32_bf16 v[92:95], v[132:135], v[180:183], v[92:95]
	v_mfma_f32_16x16x32_bf16 v[88:91], v[140:143], v[180:183], v[88:91]
	v_mfma_f32_16x16x32_bf16 v[76:79], v[132:135], v[188:191], v[76:79]
	v_mfma_f32_16x16x32_bf16 v[72:75], v[140:143], v[188:191], v[72:75]
	s_setprio 0
	s_setprio 1
	v_mfma_f32_16x16x32_bf16 v[116:119], v[144:147], v[160:163], 0
	v_mfma_f32_16x16x32_bf16 v[112:115], v[152:155], v[160:163], 0
	v_mfma_f32_16x16x32_bf16 v[100:103], v[144:147], v[168:171], 0
	v_mfma_f32_16x16x32_bf16 v[96:99], v[152:155], v[168:171], 0
	v_mfma_f32_16x16x32_bf16 v[84:87], v[144:147], v[176:179], 0
	v_mfma_f32_16x16x32_bf16 v[80:83], v[152:155], v[176:179], 0
	v_mfma_f32_16x16x32_bf16 v[68:71], v[144:147], v[184:187], 0
	v_mfma_f32_16x16x32_bf16 v[64:67], v[152:155], v[184:187], 0
	v_mfma_f32_16x16x32_bf16 v[116:119], v[148:151], v[164:167], v[116:119]
	v_mfma_f32_16x16x32_bf16 v[112:115], v[156:159], v[164:167], v[112:115]
	v_mfma_f32_16x16x32_bf16 v[100:103], v[148:151], v[172:175], v[100:103]
	v_mfma_f32_16x16x32_bf16 v[96:99], v[156:159], v[172:175], v[96:99]
	v_mfma_f32_16x16x32_bf16 v[84:87], v[148:151], v[180:183], v[84:87]
	v_mfma_f32_16x16x32_bf16 v[80:83], v[156:159], v[180:183], v[80:83]
	v_mfma_f32_16x16x32_bf16 v[68:71], v[148:151], v[188:191], v[68:71]
	v_mfma_f32_16x16x32_bf16 v[64:67], v[156:159], v[188:191], v[64:67]
	s_setprio 0
	s_barrier
	s_add_i32 m0, s54, 0x10000
	s_nop 0
	global_load_lds_dwordx4 v192, s[72:73]
	s_add_i32 m0, s54, 0x12000
	s_nop 0
	global_load_lds_dwordx4 v204, s[72:73]
	s_add_i32 m0, s54, 0x14000
	s_nop 0
	global_load_lds_dwordx4 v192, s[74:75]
	s_add_i32 m0, s54, 0x16000
	s_nop 0
	global_load_lds_dwordx4 v204, s[74:75]
	s_mov_b32 m0, s55
	s_nop 0
	global_load_lds_dwordx4 v200, s[4:5]
	s_mov_b32 m0, s56
	s_nop 0
	global_load_lds_dwordx4 v202, s[4:5]
	ds_read_b128 v[160:163], v247 offset:16384
	ds_read_b128 v[164:167], v247 offset:17408
	ds_read_b128 v[168:171], v247 offset:18432
	ds_read_b128 v[172:175], v247 offset:19456
	ds_read_b128 v[176:179], v247 offset:20480
	ds_read_b128 v[180:183], v247 offset:21504
	ds_read_b128 v[184:187], v247 offset:22528
	ds_read_b128 v[188:191], v247 offset:23552
	s_waitcnt vmcnt(8)
	s_waitcnt lgkmcnt(0)
	s_barrier
	s_setprio 1
	s_waitcnt lgkmcnt(0)
	v_mfma_f32_16x16x32_bf16 v[60:63], v[128:131], v[160:163], 0
	v_mfma_f32_16x16x32_bf16 v[56:59], v[136:139], v[160:163], 0
	v_mfma_f32_16x16x32_bf16 v[44:47], v[128:131], v[168:171], 0
	v_mfma_f32_16x16x32_bf16 v[40:43], v[136:139], v[168:171], 0
	v_mfma_f32_16x16x32_bf16 v[28:31], v[128:131], v[176:179], 0
	v_mfma_f32_16x16x32_bf16 v[24:27], v[136:139], v[176:179], 0
	v_mfma_f32_16x16x32_bf16 v[12:15], v[128:131], v[184:187], 0
	v_mfma_f32_16x16x32_bf16 v[8:11], v[136:139], v[184:187], 0
	v_mfma_f32_16x16x32_bf16 v[60:63], v[132:135], v[164:167], v[60:63]
	v_mfma_f32_16x16x32_bf16 v[56:59], v[140:143], v[164:167], v[56:59]
	v_mfma_f32_16x16x32_bf16 v[44:47], v[132:135], v[172:175], v[44:47]
	v_mfma_f32_16x16x32_bf16 v[40:43], v[140:143], v[172:175], v[40:43]
	v_mfma_f32_16x16x32_bf16 v[28:31], v[132:135], v[180:183], v[28:31]
	v_mfma_f32_16x16x32_bf16 v[24:27], v[140:143], v[180:183], v[24:27]
	v_mfma_f32_16x16x32_bf16 v[12:15], v[132:135], v[188:191], v[12:15]
	v_mfma_f32_16x16x32_bf16 v[8:11], v[140:143], v[188:191], v[8:11]
	s_setprio 0
	s_setprio 1
	v_mfma_f32_16x16x32_bf16 v[52:55], v[144:147], v[160:163], 0
	v_mfma_f32_16x16x32_bf16 v[48:51], v[152:155], v[160:163], 0
	v_mfma_f32_16x16x32_bf16 v[36:39], v[144:147], v[168:171], 0
	v_mfma_f32_16x16x32_bf16 v[32:35], v[152:155], v[168:171], 0
	v_mfma_f32_16x16x32_bf16 v[20:23], v[144:147], v[176:179], 0
	v_mfma_f32_16x16x32_bf16 v[16:19], v[152:155], v[176:179], 0
	v_mfma_f32_16x16x32_bf16 v[4:7], v[144:147], v[184:187], 0
	v_mfma_f32_16x16x32_bf16 v[0:3], v[152:155], v[184:187], 0
	v_mfma_f32_16x16x32_bf16 v[52:55], v[148:151], v[164:167], v[52:55]
	v_mfma_f32_16x16x32_bf16 v[48:51], v[156:159], v[164:167], v[48:51]
	v_mfma_f32_16x16x32_bf16 v[36:39], v[148:151], v[172:175], v[36:39]
	v_mfma_f32_16x16x32_bf16 v[32:35], v[156:159], v[172:175], v[32:35]
	v_mfma_f32_16x16x32_bf16 v[20:23], v[148:151], v[180:183], v[20:23]
	v_mfma_f32_16x16x32_bf16 v[16:19], v[156:159], v[180:183], v[16:19]
	v_mfma_f32_16x16x32_bf16 v[4:7], v[148:151], v[188:191], v[4:7]
	v_mfma_f32_16x16x32_bf16 v[0:3], v[156:159], v[188:191], v[0:3]
	s_setprio 0
	s_barrier
; #define PG8_STAGE(bufoff, gbase, voff) do { _Pragma("unroll") for (int _i = 0; _i < 2; ++_i) \
;         __builtin_amdgcn_global_load_lds((const unsigned*)((const char*)(gbase) + (voff)[_i]), (LAS unsigned*)(lds + (bufoff) + ldsw + _i * 8192), 16, 0, 0); } while (0)
; #define PG8_LDA(dst, b, h) do { _Pragma("unroll") for (int m = 0; m < 4; ++m) _Pragma("unroll") for (int k = 0; k < 2; ++k) dst[m][k] = *(const LAS bf16x8*)(lds + PG8_SA(b, h) + aoff + m * 2048 + k * 1024); } while (0)
; #define PG8_LDB(dst, b, h) do { _Pragma("unroll") for (int n = 0; n < 2; ++n) _Pragma("unroll") for (int k = 0; k < 2; ++k) dst[n][k] = *(const LAS bf16x8*)(lds + PG8_SB(b, h) + boff + n * 2048 + k * 1024); } while (0)
; #define PG8_MMA(ai, bj, At, Bt) do { __builtin_amdgcn_s_setprio(1); _Pragma("unroll") for (int m = 0; m < 4; ++m) _Pragma("unroll") for (int n = 0; n < 2; ++n) _Pragma("unroll") for (int k = 0; k < 2; ++k) \
;         acc[ai][bj][m][n] = __builtin_amdgcn_mfma_f32_16x16x32_bf16(Bt[n][k], At[m][k], acc[ai][bj][m][n], 0, 0, 0); __builtin_amdgcn_s_setprio(0); } while (0)
; #define PG8_WAIT_V(n) asm volatile("s_waitcnt vmcnt(" #n ")" ::: "memory")
; #define PG8_WAIT_L(n) asm volatile("s_waitcnt lgkmcnt(" #n ")" ::: "memory")
; #define PG8_BAR __builtin_amdgcn_s_barrier()
; #define PG8_SCHED __builtin_amdgcn_sched_barrier(0)
; template <class Epi>
; __device__ __forceinline__ void gemm_phase(LAS unsigned char* lds, const Gemm g, const StaticOrder& S, const Epi& E) {
;     ...
;             PG8_LDB(B0, 1, 0); PG8_LDB(B1, 1, 1); PG8_SCHED; PG8_LDA(At, 1, 0); PG8_STAGE(PG8_SA(0, 1), a2 + hstep, voffA);
;             PG8_WAIT_V(8); PG8_WAIT_L(0); PG8_BAR; PG8_MMA(0, 0, At, B0); PG8_MMA(0, 1, At, B1); PG8_BAR; PG8_SCHED;
;             PG8_LDA(At, 1, 1); PG8_STAGE(PG8_SB(1, 0), b3, voffB); PG8_STAGE(PG8_SB(1, 1), b3 + hstep, voffB); PG8_STAGE(PG8_SA(1, 0), a3, voffA);
;             PG8_WAIT_V(8); PG8_WAIT_L(0); PG8_BAR; PG8_MMA(1, 0, At, B0); PG8_MMA(1, 1, At, B1); PG8_BAR; PG8_SCHED;
	s_mov_b32 m0, s57
	s_nop 0
	global_load_lds_dwordx4 v200, vcc
	s_mov_b32 m0, s58
	s_nop 0
	global_load_lds_dwordx4 v202, vcc
	ds_read_b128 v[128:131], v218
	ds_read_b128 v[132:135], v218 offset:1024
	ds_read_b128 v[136:139], v218 offset:2048
	ds_read_b128 v[140:143], v218 offset:3072
	ds_read_b128 v[144:147], v219
	ds_read_b128 v[148:151], v219 offset:1024
	ds_read_b128 v[152:155], v219 offset:2048
	ds_read_b128 v[156:159], v219 offset:3072
	ds_read_b128 v[160:163], v247 offset:32768
	ds_read_b128 v[164:167], v247 offset:33792
	ds_read_b128 v[168:171], v247 offset:34816
	ds_read_b128 v[172:175], v247 offset:35840
	ds_read_b128 v[176:179], v247 offset:36864
	ds_read_b128 v[180:183], v247 offset:37888
	ds_read_b128 v[184:187], v247 offset:38912
	ds_read_b128 v[188:191], v247 offset:39936
	s_waitcnt vmcnt(8)
	s_waitcnt lgkmcnt(0)
	s_barrier
	s_setprio 1
	s_waitcnt lgkmcnt(0)
	v_mfma_f32_16x16x32_bf16 v[124:127], v[128:131], v[160:163], v[124:127]
	v_mfma_f32_16x16x32_bf16 v[120:123], v[136:139], v[160:163], v[120:123]
	v_mfma_f32_16x16x32_bf16 v[108:111], v[128:131], v[168:171], v[108:111]
	v_mfma_f32_16x16x32_bf16 v[104:107], v[136:139], v[168:171], v[104:107]
	v_mfma_f32_16x16x32_bf16 v[92:95], v[128:131], v[176:179], v[92:95]
	v_mfma_f32_16x16x32_bf16 v[88:91], v[136:139], v[176:179], v[88:91]
	v_mfma_f32_16x16x32_bf16 v[76:79], v[128:131], v[184:187], v[76:79]
	v_mfma_f32_16x16x32_bf16 v[72:75], v[136:139], v[184:187], v[72:75]
	v_mfma_f32_16x16x32_bf16 v[124:127], v[132:135], v[164:167], v[124:127]
	v_mfma_f32_16x16x32_bf16 v[120:123], v[140:143], v[164:167], v[120:123]
	v_mfma_f32_16x16x32_bf16 v[108:111], v[132:135], v[172:175], v[108:111]
	v_mfma_f32_16x16x32_bf16 v[104:107], v[140:143], v[172:175], v[104:107]
	v_mfma_f32_16x16x32_bf16 v[92:95], v[132:135], v[180:183], v[92:95]
	v_mfma_f32_16x16x32_bf16 v[88:91], v[140:143], v[180:183], v[88:91]
	v_mfma_f32_16x16x32_bf16 v[76:79], v[132:135], v[188:191], v[76:79]
	v_mfma_f32_16x16x32_bf16 v[72:75], v[140:143], v[188:191], v[72:75]
	s_setprio 0
	s_setprio 1
	v_mfma_f32_16x16x32_bf16 v[116:119], v[144:147], v[160:163], v[116:119]
	v_mfma_f32_16x16x32_bf16 v[112:115], v[152:155], v[160:163], v[112:115]
	v_mfma_f32_16x16x32_bf16 v[100:103], v[144:147], v[168:171], v[100:103]
	v_mfma_f32_16x16x32_bf16 v[96:99], v[152:155], v[168:171], v[96:99]
	v_mfma_f32_16x16x32_bf16 v[84:87], v[144:147], v[176:179], v[84:87]
	v_mfma_f32_16x16x32_bf16 v[80:83], v[152:155], v[176:179], v[80:83]
	v_mfma_f32_16x16x32_bf16 v[68:71], v[144:147], v[184:187], v[68:71]
	v_mfma_f32_16x16x32_bf16 v[64:67], v[152:155], v[184:187], v[64:67]
	v_mfma_f32_16x16x32_bf16 v[116:119], v[148:151], v[164:167], v[116:119]
	v_mfma_f32_16x16x32_bf16 v[112:115], v[156:159], v[164:167], v[112:115]
	v_mfma_f32_16x16x32_bf16 v[100:103], v[148:151], v[172:175], v[100:103]
	v_mfma_f32_16x16x32_bf16 v[96:99], v[156:159], v[172:175], v[96:99]
	v_mfma_f32_16x16x32_bf16 v[84:87], v[148:151], v[180:183], v[84:87]
	v_mfma_f32_16x16x32_bf16 v[80:83], v[156:159], v[180:183], v[80:83]
	v_mfma_f32_16x16x32_bf16 v[68:71], v[148:151], v[188:191], v[68:71]
	v_mfma_f32_16x16x32_bf16 v[64:67], v[156:159], v[188:191], v[64:67]
	s_setprio 0
	s_barrier
	s_add_i32 m0, s54, 0x17f80
	s_nop 0
	global_load_lds_dwordx4 v192, s[72:73] offset:128
	s_add_i32 m0, s54, 0x19f80
	s_nop 0
	global_load_lds_dwordx4 v204, s[72:73] offset:128
	s_add_i32 m0, s54, 0x1bf80
	s_nop 0
	global_load_lds_dwordx4 v192, s[74:75] offset:128
	s_add_i32 m0, s54, 0x1df80
	s_nop 0
	global_load_lds_dwordx4 v204, s[74:75] offset:128
	s_add_i32 m0, s59, 0xffffff80
	s_nop 0
	global_load_lds_dwordx4 v200, s[4:5] offset:128
	s_add_i32 m0, s60, 0xffffff80
	s_nop 0
	global_load_lds_dwordx4 v202, s[4:5] offset:128
	ds_read_b128 v[160:163], v247 offset:49152
	ds_read_b128 v[164:167], v247 offset:50176
	ds_read_b128 v[168:171], v247 offset:51200
	ds_read_b128 v[172:175], v247 offset:52224
	ds_read_b128 v[176:179], v247 offset:53248
	ds_read_b128 v[180:183], v247 offset:54272
	ds_read_b128 v[184:187], v247 offset:55296
	ds_read_b128 v[188:191], v247 offset:56320
	s_waitcnt vmcnt(8)
	s_waitcnt lgkmcnt(0)
	s_barrier
	s_setprio 1
	s_waitcnt lgkmcnt(0)
	v_mfma_f32_16x16x32_bf16 v[60:63], v[128:131], v[160:163], v[60:63]
	v_mfma_f32_16x16x32_bf16 v[56:59], v[136:139], v[160:163], v[56:59]
	v_mfma_f32_16x16x32_bf16 v[44:47], v[128:131], v[168:171], v[44:47]
	v_mfma_f32_16x16x32_bf16 v[40:43], v[136:139], v[168:171], v[40:43]
	v_mfma_f32_16x16x32_bf16 v[28:31], v[128:131], v[176:179], v[28:31]
	v_mfma_f32_16x16x32_bf16 v[24:27], v[136:139], v[176:179], v[24:27]
	v_mfma_f32_16x16x32_bf16 v[12:15], v[128:131], v[184:187], v[12:15]
	v_mfma_f32_16x16x32_bf16 v[8:11], v[136:139], v[184:187], v[8:11]
	v_mfma_f32_16x16x32_bf16 v[60:63], v[132:135], v[164:167], v[60:63]
	v_mfma_f32_16x16x32_bf16 v[56:59], v[140:143], v[164:167], v[56:59]
	v_mfma_f32_16x16x32_bf16 v[44:47], v[132:135], v[172:175], v[44:47]
	v_mfma_f32_16x16x32_bf16 v[40:43], v[140:143], v[172:175], v[40:43]
	v_mfma_f32_16x16x32_bf16 v[28:31], v[132:135], v[180:183], v[28:31]
	v_mfma_f32_16x16x32_bf16 v[24:27], v[140:143], v[180:183], v[24:27]
	v_mfma_f32_16x16x32_bf16 v[12:15], v[132:135], v[188:191], v[12:15]
	v_mfma_f32_16x16x32_bf16 v[8:11], v[140:143], v[188:191], v[8:11]
	s_setprio 0
	s_setprio 1
	v_mfma_f32_16x16x32_bf16 v[52:55], v[144:147], v[160:163], v[52:55]
	v_mfma_f32_16x16x32_bf16 v[48:51], v[152:155], v[160:163], v[48:51]
	v_mfma_f32_16x16x32_bf16 v[36:39], v[144:147], v[168:171], v[36:39]
	v_mfma_f32_16x16x32_bf16 v[32:35], v[152:155], v[168:171], v[32:35]
	v_mfma_f32_16x16x32_bf16 v[20:23], v[144:147], v[176:179], v[20:23]
	v_mfma_f32_16x16x32_bf16 v[16:19], v[152:155], v[176:179], v[16:19]
	v_mfma_f32_16x16x32_bf16 v[4:7], v[144:147], v[184:187], v[4:7]
	v_mfma_f32_16x16x32_bf16 v[0:3], v[152:155], v[184:187], v[0:3]
	v_mfma_f32_16x16x32_bf16 v[52:55], v[148:151], v[164:167], v[52:55]
	v_mfma_f32_16x16x32_bf16 v[48:51], v[156:159], v[164:167], v[48:51]
	v_mfma_f32_16x16x32_bf16 v[36:39], v[148:151], v[172:175], v[36:39]
	v_mfma_f32_16x16x32_bf16 v[32:35], v[156:159], v[172:175], v[32:35]
	v_mfma_f32_16x16x32_bf16 v[20:23], v[148:151], v[180:183], v[20:23]
	v_mfma_f32_16x16x32_bf16 v[16:19], v[156:159], v[180:183], v[16:19]
	v_mfma_f32_16x16x32_bf16 v[4:7], v[148:151], v[188:191], v[4:7]
	v_mfma_f32_16x16x32_bf16 v[0:3], v[156:159], v[188:191], v[0:3]
	s_setprio 0
	s_barrier
	s_add_u32 s0, s0, 0x100
	s_addc_u32 s1, s1, 0
	s_add_u32 s6, s6, 0x100
	s_addc_u32 s7, s7, 0
	s_cmp_ge_u32 s71, s61
	s_mov_b32 s4, s71
	s_cbranch_scc1 .Lk_done
; #define PG8_STAGE(bufoff, gbase, voff) do { _Pragma("unroll") for (int _i = 0; _i < 2; ++_i) \
;         __builtin_amdgcn_global_load_lds((const unsigned*)((const char*)(gbase) + (voff)[_i]), (LAS unsigned*)(lds + (bufoff) + ldsw + _i * 8192), 16, 0, 0); } while (0)
; #define PG8_LDA(dst, b, h) do { _Pragma("unroll") for (int m = 0; m < 4; ++m) _Pragma("unroll") for (int k = 0; k < 2; ++k) dst[m][k] = *(const LAS bf16x8*)(lds + PG8_SA(b, h) + aoff + m * 2048 + k * 1024); } while (0)
; #define PG8_LDB(dst, b, h) do { _Pragma("unroll") for (int n = 0; n < 2; ++n) _Pragma("unroll") for (int k = 0; k < 2; ++k) dst[n][k] = *(const LAS bf16x8*)(lds + PG8_SB(b, h) + boff + n * 2048 + k * 1024); } while (0)
; #define PG8_MMA(ai, bj, At, Bt) do { __builtin_amdgcn_s_setprio(1); _Pragma("unroll") for (int m = 0; m < 4; ++m) _Pragma("unroll") for (int n = 0; n < 2; ++n) _Pragma("unroll") for (int k = 0; k < 2; ++k) \
;         acc[ai][bj][m][n] = __builtin_amdgcn_mfma_f32_16x16x32_bf16(Bt[n][k], At[m][k], acc[ai][bj][m][n], 0, 0, 0); __builtin_amdgcn_s_setprio(0); } while (0)
; #define PG8_WAIT_V(n) asm volatile("s_waitcnt vmcnt(" #n ")" ::: "memory")
; #define PG8_WAIT_L(n) asm volatile("s_waitcnt lgkmcnt(" #n ")" ::: "memory")
; #define PG8_BAR __builtin_amdgcn_s_barrier()
; #define PG8_SCHED __builtin_amdgcn_sched_barrier(0)
; template <class Epi>
; __device__ __forceinline__ void gemm_phase(LAS unsigned char* lds, const Gemm g, const StaticOrder& S, const Epi& E) {
;     ...
;         for (int t = 0; t < nt; t += 2) {
;             const bool last = (t == nt - 2);
;             const char* a1 = cA + (size_t)(t + 1) * kstep;
;             const char* a2 = last ? nA : cA + (size_t)(t + 2) * kstep; const char* b2 = last ? nB : cB + (size_t)(t + 2) * kstep;
;             const char* a3 = a2 + kstep; const char* b3 = b2 + kstep;
;             PG8_LDB(B0, 0, 0); PG8_LDB(B1, 0, 1); PG8_SCHED; PG8_LDA(At, 0, 0); PG8_STAGE(PG8_SA(1, 1), a1 + hstep, voffA);
;             PG8_WAIT_V(8); PG8_WAIT_L(0); PG8_BAR; PG8_MMA(0, 0, At, B0); PG8_MMA(0, 1, At, B1); PG8_BAR; PG8_SCHED;
;             PG8_LDA(At, 0, 1); PG8_STAGE(PG8_SB(0, 0), b2, voffB); PG8_STAGE(PG8_SB(0, 1), b2 + hstep, voffB); PG8_STAGE(PG8_SA(0, 0), a2, voffA);
;             PG8_WAIT_V(8); PG8_WAIT_L(0); PG8_BAR; PG8_MMA(1, 0, At, B0); PG8_MMA(1, 1, At, B1); PG8_BAR; PG8_SCHED;
.LBB0_222:
	s_add_i32 s71, s4, 2
	s_add_u32 s72, s0, 0x80
	s_addc_u32 s5, s1, 0
	s_cmp_eq_u32 s62, s4
	s_cselect_b32 s5, s49, s5
	s_cselect_b32 s4, s48, s72
	s_cselect_b32 s73, s51, s7
	s_cselect_b32 s72, s50, s6
	s_add_u32 s74, s72, s2
	s_addc_u32 s75, s73, 0
	s_add_u32 vcc_lo, s4, s2
	s_addc_u32 vcc_hi, s5, 0
	s_add_i32 m0, s55, 0xc000
	s_nop 0
	global_load_lds_dwordx4 v208, s[0:1]
	s_add_i32 m0, s55, 0xe000
	s_nop 0
	global_load_lds_dwordx4 v210, s[0:1]
	ds_read_b128 v[128:131], v216
	ds_read_b128 v[132:135], v216 offset:1024
	ds_read_b128 v[136:139], v216 offset:2048
	ds_read_b128 v[140:143], v216 offset:3072
	ds_read_b128 v[144:147], v217
	ds_read_b128 v[148:151], v217 offset:1024
	ds_read_b128 v[152:155], v217 offset:2048
	ds_read_b128 v[156:159], v217 offset:3072
	ds_read_b128 v[160:163], v247
	ds_read_b128 v[164:167], v247 offset:1024
	ds_read_b128 v[168:171], v247 offset:2048
	ds_read_b128 v[172:175], v247 offset:3072
	ds_read_b128 v[176:179], v247 offset:4096
	ds_read_b128 v[180:183], v247 offset:5120
	ds_read_b128 v[184:187], v247 offset:6144
	ds_read_b128 v[188:191], v247 offset:7168
	s_waitcnt vmcnt(8)
	s_waitcnt lgkmcnt(0)
	s_barrier
	s_setprio 1
	s_waitcnt lgkmcnt(0)
	v_mfma_f32_16x16x32_bf16 v[124:127], v[128:131], v[160:163], v[124:127]
	v_mfma_f32_16x16x32_bf16 v[120:123], v[136:139], v[160:163], v[120:123]
	v_mfma_f32_16x16x32_bf16 v[108:111], v[128:131], v[168:171], v[108:111]
	v_mfma_f32_16x16x32_bf16 v[104:107], v[136:139], v[168:171], v[104:107]
	v_mfma_f32_16x16x32_bf16 v[92:95], v[128:131], v[176:179], v[92:95]
	v_mfma_f32_16x16x32_bf16 v[88:91], v[136:139], v[176:179], v[88:91]
	v_mfma_f32_16x16x32_bf16 v[76:79], v[128:131], v[184:187], v[76:79]
	v_mfma_f32_16x16x32_bf16 v[72:75], v[136:139], v[184:187], v[72:75]
	v_mfma_f32_16x16x32_bf16 v[124:127], v[132:135], v[164:167], v[124:127]
	v_mfma_f32_16x16x32_bf16 v[120:123], v[140:143], v[164:167], v[120:123]
	v_mfma_f32_16x16x32_bf16 v[108:111], v[132:135], v[172:175], v[108:111]
	v_mfma_f32_16x16x32_bf16 v[104:107], v[140:143], v[172:175], v[104:107]
	v_mfma_f32_16x16x32_bf16 v[92:95], v[132:135], v[180:183], v[92:95]
	v_mfma_f32_16x16x32_bf16 v[88:91], v[140:143], v[180:183], v[88:91]
	v_mfma_f32_16x16x32_bf16 v[76:79], v[132:135], v[188:191], v[76:79]
	v_mfma_f32_16x16x32_bf16 v[72:75], v[140:143], v[188:191], v[72:75]
	s_setprio 0
	s_setprio 1
	v_mfma_f32_16x16x32_bf16 v[116:119], v[144:147], v[160:163], v[116:119]
	v_mfma_f32_16x16x32_bf16 v[112:115], v[152:155], v[160:163], v[112:115]
	v_mfma_f32_16x16x32_bf16 v[100:103], v[144:147], v[168:171], v[100:103]
	v_mfma_f32_16x16x32_bf16 v[96:99], v[152:155], v[168:171], v[96:99]
	v_mfma_f32_16x16x32_bf16 v[84:87], v[144:147], v[176:179], v[84:87]
	v_mfma_f32_16x16x32_bf16 v[80:83], v[152:155], v[176:179], v[80:83]
	v_mfma_f32_16x16x32_bf16 v[68:71], v[144:147], v[184:187], v[68:71]
	v_mfma_f32_16x16x32_bf16 v[64:67], v[152:155], v[184:187], v[64:67]
	v_mfma_f32_16x16x32_bf16 v[116:119], v[148:151], v[164:167], v[116:119]
	v_mfma_f32_16x16x32_bf16 v[112:115], v[156:159], v[164:167], v[112:115]
	v_mfma_f32_16x16x32_bf16 v[100:103], v[148:151], v[172:175], v[100:103]
	v_mfma_f32_16x16x32_bf16 v[96:99], v[156:159], v[172:175], v[96:99]
	v_mfma_f32_16x16x32_bf16 v[84:87], v[148:151], v[180:183], v[84:87]
	v_mfma_f32_16x16x32_bf16 v[80:83], v[156:159], v[180:183], v[80:83]
	v_mfma_f32_16x16x32_bf16 v[68:71], v[148:151], v[188:191], v[68:71]
	v_mfma_f32_16x16x32_bf16 v[64:67], v[156:159], v[188:191], v[64:67]
	s_setprio 0
	s_barrier
	s_add_i32 m0, s54, 0x10000
	s_nop 0
	global_load_lds_dwordx4 v192, s[72:73]
	s_add_i32 m0, s54, 0x12000
	s_nop 0
	global_load_lds_dwordx4 v204, s[72:73]
	s_add_i32 m0, s54, 0x14000
	s_nop 0
	global_load_lds_dwordx4 v192, s[74:75]
	s_add_i32 m0, s54, 0x16000
	s_nop 0
	global_load_lds_dwordx4 v204, s[74:75]
	s_mov_b32 m0, s55
	s_nop 0
	global_load_lds_dwordx4 v200, s[4:5]
	s_mov_b32 m0, s56
	s_nop 0
	global_load_lds_dwordx4 v202, s[4:5]
	ds_read_b128 v[160:163], v247 offset:16384
	ds_read_b128 v[164:167], v247 offset:17408
	ds_read_b128 v[168:171], v247 offset:18432
	ds_read_b128 v[172:175], v247 offset:19456
	ds_read_b128 v[176:179], v247 offset:20480
	ds_read_b128 v[180:183], v247 offset:21504
	ds_read_b128 v[184:187], v247 offset:22528
	ds_read_b128 v[188:191], v247 offset:23552
	s_waitcnt vmcnt(8)
	s_waitcnt lgkmcnt(0)
	s_barrier
	s_setprio 1
	s_waitcnt lgkmcnt(0)
	v_mfma_f32_16x16x32_bf16 v[60:63], v[128:131], v[160:163], v[60:63]
	v_mfma_f32_16x16x32_bf16 v[56:59], v[136:139], v[160:163], v[56:59]
	v_mfma_f32_16x16x32_bf16 v[44:47], v[128:131], v[168:171], v[44:47]
	v_mfma_f32_16x16x32_bf16 v[40:43], v[136:139], v[168:171], v[40:43]
	v_mfma_f32_16x16x32_bf16 v[28:31], v[128:131], v[176:179], v[28:31]
	v_mfma_f32_16x16x32_bf16 v[24:27], v[136:139], v[176:179], v[24:27]
	v_mfma_f32_16x16x32_bf16 v[12:15], v[128:131], v[184:187], v[12:15]
	v_mfma_f32_16x16x32_bf16 v[8:11], v[136:139], v[184:187], v[8:11]
	v_mfma_f32_16x16x32_bf16 v[60:63], v[132:135], v[164:167], v[60:63]
	v_mfma_f32_16x16x32_bf16 v[56:59], v[140:143], v[164:167], v[56:59]
	v_mfma_f32_16x16x32_bf16 v[44:47], v[132:135], v[172:175], v[44:47]
	v_mfma_f32_16x16x32_bf16 v[40:43], v[140:143], v[172:175], v[40:43]
	v_mfma_f32_16x16x32_bf16 v[28:31], v[132:135], v[180:183], v[28:31]
	v_mfma_f32_16x16x32_bf16 v[24:27], v[140:143], v[180:183], v[24:27]
	v_mfma_f32_16x16x32_bf16 v[12:15], v[132:135], v[188:191], v[12:15]
	v_mfma_f32_16x16x32_bf16 v[8:11], v[140:143], v[188:191], v[8:11]
	s_setprio 0
	s_setprio 1
	v_mfma_f32_16x16x32_bf16 v[52:55], v[144:147], v[160:163], v[52:55]
	v_mfma_f32_16x16x32_bf16 v[48:51], v[152:155], v[160:163], v[48:51]
	v_mfma_f32_16x16x32_bf16 v[36:39], v[144:147], v[168:171], v[36:39]
	v_mfma_f32_16x16x32_bf16 v[32:35], v[152:155], v[168:171], v[32:35]
	v_mfma_f32_16x16x32_bf16 v[20:23], v[144:147], v[176:179], v[20:23]
	v_mfma_f32_16x16x32_bf16 v[16:19], v[152:155], v[176:179], v[16:19]
	v_mfma_f32_16x16x32_bf16 v[4:7], v[144:147], v[184:187], v[4:7]
	v_mfma_f32_16x16x32_bf16 v[0:3], v[152:155], v[184:187], v[0:3]
	v_mfma_f32_16x16x32_bf16 v[52:55], v[148:151], v[164:167], v[52:55]
	v_mfma_f32_16x16x32_bf16 v[48:51], v[156:159], v[164:167], v[48:51]
	v_mfma_f32_16x16x32_bf16 v[36:39], v[148:151], v[172:175], v[36:39]
	v_mfma_f32_16x16x32_bf16 v[32:35], v[156:159], v[172:175], v[32:35]
	v_mfma_f32_16x16x32_bf16 v[20:23], v[148:151], v[180:183], v[20:23]
	v_mfma_f32_16x16x32_bf16 v[16:19], v[156:159], v[180:183], v[16:19]
	v_mfma_f32_16x16x32_bf16 v[4:7], v[148:151], v[188:191], v[4:7]
	v_mfma_f32_16x16x32_bf16 v[0:3], v[156:159], v[188:191], v[0:3]
	s_setprio 0
	s_barrier
; #define PG8_STAGE(bufoff, gbase, voff) do { _Pragma("unroll") for (int _i = 0; _i < 2; ++_i) \
;         __builtin_amdgcn_global_load_lds((const unsigned*)((const char*)(gbase) + (voff)[_i]), (LAS unsigned*)(lds + (bufoff) + ldsw + _i * 8192), 16, 0, 0); } while (0)
; #define PG8_LDA(dst, b, h) do { _Pragma("unroll") for (int m = 0; m < 4; ++m) _Pragma("unroll") for (int k = 0; k < 2; ++k) dst[m][k] = *(const LAS bf16x8*)(lds + PG8_SA(b, h) + aoff + m * 2048 + k * 1024); } while (0)
; #define PG8_LDB(dst, b, h) do { _Pragma("unroll") for (int n = 0; n < 2; ++n) _Pragma("unroll") for (int k = 0; k < 2; ++k) dst[n][k] = *(const LAS bf16x8*)(lds + PG8_SB(b, h) + boff + n * 2048 + k * 1024); } while (0)
; #define PG8_MMA(ai, bj, At, Bt) do { __builtin_amdgcn_s_setprio(1); _Pragma("unroll") for (int m = 0; m < 4; ++m) _Pragma("unroll") for (int n = 0; n < 2; ++n) _Pragma("unroll") for (int k = 0; k < 2; ++k) \
;         acc[ai][bj][m][n] = __builtin_amdgcn_mfma_f32_16x16x32_bf16(Bt[n][k], At[m][k], acc[ai][bj][m][n], 0, 0, 0); __builtin_amdgcn_s_setprio(0); } while (0)
; #define PG8_WAIT_V(n) asm volatile("s_waitcnt vmcnt(" #n ")" ::: "memory")
; #define PG8_WAIT_L(n) asm volatile("s_waitcnt lgkmcnt(" #n ")" ::: "memory")
; #define PG8_BAR __builtin_amdgcn_s_barrier()
; #define PG8_SCHED __builtin_amdgcn_sched_barrier(0)
; template <class Epi>
; __device__ __forceinline__ void gemm_phase(LAS unsigned char* lds, const Gemm g, const StaticOrder& S, const Epi& E) {
;     ...
;             PG8_LDB(B0, 1, 0); PG8_LDB(B1, 1, 1); PG8_SCHED; PG8_LDA(At, 1, 0); PG8_STAGE(PG8_SA(0, 1), a2 + hstep, voffA);
;             PG8_WAIT_V(8); PG8_WAIT_L(0); PG8_BAR; PG8_MMA(0, 0, At, B0); PG8_MMA(0, 1, At, B1); PG8_BAR; PG8_SCHED;
;             PG8_LDA(At, 1, 1); PG8_STAGE(PG8_SB(1, 0), b3, voffB); PG8_STAGE(PG8_SB(1, 1), b3 + hstep, voffB); PG8_STAGE(PG8_SA(1, 0), a3, voffA);
;             PG8_WAIT_V(8); PG8_WAIT_L(0); PG8_BAR; PG8_MMA(1, 0, At, B0); PG8_MMA(1, 1, At, B1); PG8_BAR; PG8_SCHED;
;         }
	s_mov_b32 m0, s57
	s_nop 0
	global_load_lds_dwordx4 v200, vcc
	s_mov_b32 m0, s58
	s_nop 0
	global_load_lds_dwordx4 v202, vcc
	ds_read_b128 v[128:131], v218
	ds_read_b128 v[132:135], v218 offset:1024
	ds_read_b128 v[136:139], v218 offset:2048
	ds_read_b128 v[140:143], v218 offset:3072
	ds_read_b128 v[144:147], v219
	ds_read_b128 v[148:151], v219 offset:1024
	ds_read_b128 v[152:155], v219 offset:2048
	ds_read_b128 v[156:159], v219 offset:3072
	ds_read_b128 v[160:163], v247 offset:32768
	ds_read_b128 v[164:167], v247 offset:33792
	ds_read_b128 v[168:171], v247 offset:34816
	ds_read_b128 v[172:175], v247 offset:35840
	ds_read_b128 v[176:179], v247 offset:36864
	ds_read_b128 v[180:183], v247 offset:37888
	ds_read_b128 v[184:187], v247 offset:38912
	ds_read_b128 v[188:191], v247 offset:39936
	s_waitcnt vmcnt(8)
	s_waitcnt lgkmcnt(0)
	s_barrier
	s_setprio 1
	s_waitcnt lgkmcnt(0)
	v_mfma_f32_16x16x32_bf16 v[124:127], v[128:131], v[160:163], v[124:127]
	v_mfma_f32_16x16x32_bf16 v[120:123], v[136:139], v[160:163], v[120:123]
	v_mfma_f32_16x16x32_bf16 v[108:111], v[128:131], v[168:171], v[108:111]
	v_mfma_f32_16x16x32_bf16 v[104:107], v[136:139], v[168:171], v[104:107]
	v_mfma_f32_16x16x32_bf16 v[92:95], v[128:131], v[176:179], v[92:95]
	v_mfma_f32_16x16x32_bf16 v[88:91], v[136:139], v[176:179], v[88:91]
	v_mfma_f32_16x16x32_bf16 v[76:79], v[128:131], v[184:187], v[76:79]
	v_mfma_f32_16x16x32_bf16 v[72:75], v[136:139], v[184:187], v[72:75]
	v_mfma_f32_16x16x32_bf16 v[124:127], v[132:135], v[164:167], v[124:127]
	v_mfma_f32_16x16x32_bf16 v[120:123], v[140:143], v[164:167], v[120:123]
	v_mfma_f32_16x16x32_bf16 v[108:111], v[132:135], v[172:175], v[108:111]
	v_mfma_f32_16x16x32_bf16 v[104:107], v[140:143], v[172:175], v[104:107]
	v_mfma_f32_16x16x32_bf16 v[92:95], v[132:135], v[180:183], v[92:95]
	v_mfma_f32_16x16x32_bf16 v[88:91], v[140:143], v[180:183], v[88:91]
	v_mfma_f32_16x16x32_bf16 v[76:79], v[132:135], v[188:191], v[76:79]
	v_mfma_f32_16x16x32_bf16 v[72:75], v[140:143], v[188:191], v[72:75]
	s_setprio 0
	s_setprio 1
	v_mfma_f32_16x16x32_bf16 v[116:119], v[144:147], v[160:163], v[116:119]
	v_mfma_f32_16x16x32_bf16 v[112:115], v[152:155], v[160:163], v[112:115]
	v_mfma_f32_16x16x32_bf16 v[100:103], v[144:147], v[168:171], v[100:103]
	v_mfma_f32_16x16x32_bf16 v[96:99], v[152:155], v[168:171], v[96:99]
	v_mfma_f32_16x16x32_bf16 v[84:87], v[144:147], v[176:179], v[84:87]
	v_mfma_f32_16x16x32_bf16 v[80:83], v[152:155], v[176:179], v[80:83]
	v_mfma_f32_16x16x32_bf16 v[68:71], v[144:147], v[184:187], v[68:71]
	v_mfma_f32_16x16x32_bf16 v[64:67], v[152:155], v[184:187], v[64:67]
	v_mfma_f32_16x16x32_bf16 v[116:119], v[148:151], v[164:167], v[116:119]
	v_mfma_f32_16x16x32_bf16 v[112:115], v[156:159], v[164:167], v[112:115]
	v_mfma_f32_16x16x32_bf16 v[100:103], v[148:151], v[172:175], v[100:103]
	v_mfma_f32_16x16x32_bf16 v[96:99], v[156:159], v[172:175], v[96:99]
	v_mfma_f32_16x16x32_bf16 v[84:87], v[148:151], v[180:183], v[84:87]
	v_mfma_f32_16x16x32_bf16 v[80:83], v[156:159], v[180:183], v[80:83]
	v_mfma_f32_16x16x32_bf16 v[68:71], v[148:151], v[188:191], v[68:71]
	v_mfma_f32_16x16x32_bf16 v[64:67], v[156:159], v[188:191], v[64:67]
	s_setprio 0
	s_barrier
	s_add_i32 m0, s54, 0x17f80
	s_nop 0
	global_load_lds_dwordx4 v192, s[72:73] offset:128
	s_add_i32 m0, s54, 0x19f80
	s_nop 0
	global_load_lds_dwordx4 v204, s[72:73] offset:128
	s_add_i32 m0, s54, 0x1bf80
	s_nop 0
	global_load_lds_dwordx4 v192, s[74:75] offset:128
	s_add_i32 m0, s54, 0x1df80
	s_nop 0
	global_load_lds_dwordx4 v204, s[74:75] offset:128
	s_add_i32 m0, s59, 0xffffff80
	s_nop 0
	global_load_lds_dwordx4 v200, s[4:5] offset:128
	s_add_i32 m0, s60, 0xffffff80
	s_nop 0
	global_load_lds_dwordx4 v202, s[4:5] offset:128
	ds_read_b128 v[160:163], v247 offset:49152
	ds_read_b128 v[164:167], v247 offset:50176
	ds_read_b128 v[168:171], v247 offset:51200
	ds_read_b128 v[172:175], v247 offset:52224
	ds_read_b128 v[176:179], v247 offset:53248
	ds_read_b128 v[180:183], v247 offset:54272
	ds_read_b128 v[184:187], v247 offset:55296
	ds_read_b128 v[188:191], v247 offset:56320
	s_waitcnt vmcnt(8)
	s_waitcnt lgkmcnt(0)
	s_barrier
	s_setprio 1
	s_waitcnt lgkmcnt(0)
	v_mfma_f32_16x16x32_bf16 v[60:63], v[128:131], v[160:163], v[60:63]
	v_mfma_f32_16x16x32_bf16 v[56:59], v[136:139], v[160:163], v[56:59]
	v_mfma_f32_16x16x32_bf16 v[44:47], v[128:131], v[168:171], v[44:47]
	v_mfma_f32_16x16x32_bf16 v[40:43], v[136:139], v[168:171], v[40:43]
	v_mfma_f32_16x16x32_bf16 v[28:31], v[128:131], v[176:179], v[28:31]
	v_mfma_f32_16x16x32_bf16 v[24:27], v[136:139], v[176:179], v[24:27]
	v_mfma_f32_16x16x32_bf16 v[12:15], v[128:131], v[184:187], v[12:15]
	v_mfma_f32_16x16x32_bf16 v[8:11], v[136:139], v[184:187], v[8:11]
	v_mfma_f32_16x16x32_bf16 v[60:63], v[132:135], v[164:167], v[60:63]
	v_mfma_f32_16x16x32_bf16 v[56:59], v[140:143], v[164:167], v[56:59]
	v_mfma_f32_16x16x32_bf16 v[44:47], v[132:135], v[172:175], v[44:47]
	v_mfma_f32_16x16x32_bf16 v[40:43], v[140:143], v[172:175], v[40:43]
	v_mfma_f32_16x16x32_bf16 v[28:31], v[132:135], v[180:183], v[28:31]
	v_mfma_f32_16x16x32_bf16 v[24:27], v[140:143], v[180:183], v[24:27]
	v_mfma_f32_16x16x32_bf16 v[12:15], v[132:135], v[188:191], v[12:15]
	v_mfma_f32_16x16x32_bf16 v[8:11], v[140:143], v[188:191], v[8:11]
	s_setprio 0
	s_setprio 1
	v_mfma_f32_16x16x32_bf16 v[52:55], v[144:147], v[160:163], v[52:55]
	v_mfma_f32_16x16x32_bf16 v[48:51], v[152:155], v[160:163], v[48:51]
	v_mfma_f32_16x16x32_bf16 v[36:39], v[144:147], v[168:171], v[36:39]
	v_mfma_f32_16x16x32_bf16 v[32:35], v[152:155], v[168:171], v[32:35]
	v_mfma_f32_16x16x32_bf16 v[20:23], v[144:147], v[176:179], v[20:23]
	v_mfma_f32_16x16x32_bf16 v[16:19], v[152:155], v[176:179], v[16:19]
	v_mfma_f32_16x16x32_bf16 v[4:7], v[144:147], v[184:187], v[4:7]
	v_mfma_f32_16x16x32_bf16 v[0:3], v[152:155], v[184:187], v[0:3]
	v_mfma_f32_16x16x32_bf16 v[52:55], v[148:151], v[164:167], v[52:55]
	v_mfma_f32_16x16x32_bf16 v[48:51], v[156:159], v[164:167], v[48:51]
	v_mfma_f32_16x16x32_bf16 v[36:39], v[148:151], v[172:175], v[36:39]
	v_mfma_f32_16x16x32_bf16 v[32:35], v[156:159], v[172:175], v[32:35]
	v_mfma_f32_16x16x32_bf16 v[20:23], v[148:151], v[180:183], v[20:23]
	v_mfma_f32_16x16x32_bf16 v[16:19], v[156:159], v[180:183], v[16:19]
	v_mfma_f32_16x16x32_bf16 v[4:7], v[148:151], v[188:191], v[4:7]
	v_mfma_f32_16x16x32_bf16 v[0:3], v[156:159], v[188:191], v[0:3]
	s_setprio 0
	s_barrier
	s_add_u32 s0, s0, 0x100
	s_addc_u32 s1, s1, 0
	s_add_u32 s6, s6, 0x100
	s_addc_u32 s7, s7, 0
	s_cmp_ge_u32 s71, s61
	s_mov_b32 s4, s71
	s_cbranch_scc0 .LBB0_222
